# attention: when the short body's test fails it fetches the V fragments and continues in the ordinary body with S already computed (no recompute, no rescale pass)
# baseline (speedup 1.0000x reference)
.Lat1_probe:
	ds_read_b128 v[160:163], v237 offset:8192
	ds_read_b128 v[164:167], v189
	ds_read_b128 v[202:205], v235 offset:8192
	ds_read_b128 v[244:247], v189 offset:4096
	ds_read_b128 v[248:251], v236 offset:8192
	ds_read_b128 v[252:255], v189 offset:1024
	s_waitcnt lgkmcnt(4)
	v_mfma_f32_32x32x16_bf16 v[144:159], v[160:163], v[164:167], v[128:143]
	s_waitcnt lgkmcnt(2)
	v_mfma_f32_32x32x16_bf16 v[160:175], v[202:205], v[244:247], v[128:143]
	ds_read_b128 v[202:205], v234 offset:8192
	ds_read_b128 v[244:247], v189 offset:5120
	v_add_u32_e32 v215, s40, v185
	v_add_u32_e32 v215, 0xe0, v215
	v_cvt_f32_i32_e32 v215, v215
	v_add_f32_e32 v227, 0x41000000, v199
	v_mul_f32_e32 v200, v184, v215
	v_add_f32_e32 v215, 0x41000000, v201
	s_waitcnt lgkmcnt(2)
	v_mfma_f32_32x32x16_bf16 v[144:159], v[248:251], v[252:255], v[144:159]
	ds_read_b128 v[248:251], v241 offset:8192
	ds_read_b128 v[252:255], v189 offset:2048
	s_waitcnt lgkmcnt(2)
	v_mfma_f32_32x32x16_bf16 v[160:175], v[202:205], v[244:247], v[160:175]
	ds_read_b128 v[202:205], v239 offset:8192
	ds_read_b128 v[244:247], v189 offset:6144
	s_waitcnt lgkmcnt(2)
	v_mfma_f32_32x32x16_bf16 v[144:159], v[248:251], v[252:255], v[144:159]
	ds_read_b128 v[248:251], v240 offset:8192
	ds_read_b128 v[252:255], v189 offset:3072
	s_waitcnt lgkmcnt(2)
	v_mfma_f32_32x32x16_bf16 v[160:175], v[202:205], v[244:247], v[160:175]
	ds_read_b128 v[202:205], v238 offset:8192
	ds_read_b128 v[244:247], v189 offset:7168
	s_waitcnt lgkmcnt(2)
	v_mfma_f32_32x32x16_bf16 v[144:159], v[248:251], v[252:255], v[144:159]
	s_waitcnt lgkmcnt(0)
	v_mfma_f32_32x32x16_bf16 v[160:175], v[202:205], v[244:247], v[160:175]
	s_nop 7
	s_nop 7
	v_max3_f32 v217, v144, v145, v146
	v_max3_f32 v219, v160, v161, v162
	v_max3_f32 v221, v147, v148, v149
	v_max3_f32 v225, v163, v164, v165
	v_max3_f32 v223, v150, v151, v152
	v_max3_f32 v229, v166, v167, v168
	v_max3_f32 v217, v217, v221, v223
	v_max3_f32 v219, v219, v225, v229
	v_max3_f32 v221, v153, v154, v155
	v_max3_f32 v225, v169, v170, v171
	v_max3_f32 v223, v156, v157, v158
	v_max3_f32 v229, v172, v173, v174
	v_max3_f32 v221, v221, v223, v159
	v_max3_f32 v225, v225, v229, v175
	v_max_f32_e32 v217, v217, v221
	v_max_f32_e32 v219, v219, v225
	v_add_f32_e32 v221, v200, v217
	v_add_f32_e32 v225, v200, v219
	v_sub_f32_e32 v223, v221, v227
	v_sub_f32_e32 v229, v225, v215
	v_max_f32_e32 v223, v223, v229
	v_add_f32_e32 v223, 0x43080000, v223
	v_cmp_nlt_f32_e64 s[98:99], v223, 0
	s_nop 3
	s_cmp_eq_u64 s[98:99], 0
	s_cbranch_scc1 .Lat1_skip
	s_mov_b32 s51, 0
	ds_read_b64_tr_b16 v[202:203], v216 offset:8192
	ds_read_b64_tr_b16 v[204:205], v218 offset:8192
	ds_read_b64_tr_b16 v[244:245], v220 offset:8192
	ds_read_b64_tr_b16 v[246:247], v222 offset:8192
	ds_read_b64_tr_b16 v[248:249], v224 offset:8192
	ds_read_b64_tr_b16 v[250:251], v226 offset:8192
	ds_read_b64_tr_b16 v[252:253], v228 offset:8192
	ds_read_b64_tr_b16 v[254:255], v230 offset:8192
	s_branch .Lat1_go
.Lat2_probe:
	ds_read_b128 v[160:163], v237
	ds_read_b128 v[164:167], v189
	ds_read_b128 v[202:205], v235
	ds_read_b128 v[244:247], v189 offset:4096
	ds_read_b128 v[248:251], v236
	ds_read_b128 v[252:255], v189 offset:1024
	s_waitcnt lgkmcnt(4)
	v_mfma_f32_32x32x16_bf16 v[144:159], v[160:163], v[164:167], v[128:143]
	s_waitcnt lgkmcnt(2)
	v_mfma_f32_32x32x16_bf16 v[160:175], v[202:205], v[244:247], v[128:143]
	ds_read_b128 v[202:205], v234
	ds_read_b128 v[244:247], v189 offset:5120
	v_add_u32_e32 v215, s40, v185
	v_add_u32_e32 v215, 0xc0, v215
	v_cvt_f32_i32_e32 v215, v215
	v_add_f32_e32 v227, 0x41000000, v199
	v_mul_f32_e32 v200, v184, v215
	v_add_f32_e32 v215, 0x41000000, v201
	s_waitcnt lgkmcnt(2)
	v_mfma_f32_32x32x16_bf16 v[144:159], v[248:251], v[252:255], v[144:159]
	ds_read_b128 v[248:251], v241
	ds_read_b128 v[252:255], v189 offset:2048
	s_waitcnt lgkmcnt(2)
	v_mfma_f32_32x32x16_bf16 v[160:175], v[202:205], v[244:247], v[160:175]
	ds_read_b128 v[202:205], v239
	ds_read_b128 v[244:247], v189 offset:6144
	s_waitcnt lgkmcnt(2)
	v_mfma_f32_32x32x16_bf16 v[144:159], v[248:251], v[252:255], v[144:159]
	ds_read_b128 v[248:251], v240
	ds_read_b128 v[252:255], v189 offset:3072
	s_waitcnt lgkmcnt(2)
	v_mfma_f32_32x32x16_bf16 v[160:175], v[202:205], v[244:247], v[160:175]
	ds_read_b128 v[202:205], v238
	ds_read_b128 v[244:247], v189 offset:7168
	s_waitcnt lgkmcnt(2)
	v_mfma_f32_32x32x16_bf16 v[144:159], v[248:251], v[252:255], v[144:159]
	s_waitcnt lgkmcnt(0)
	v_mfma_f32_32x32x16_bf16 v[160:175], v[202:205], v[244:247], v[160:175]
	s_nop 7
	s_nop 7
	v_max3_f32 v217, v144, v145, v146
	v_max3_f32 v219, v160, v161, v162
	v_max3_f32 v221, v147, v148, v149
	v_max3_f32 v225, v163, v164, v165
	v_max3_f32 v223, v150, v151, v152
	v_max3_f32 v229, v166, v167, v168
	v_max3_f32 v217, v217, v221, v223
	v_max3_f32 v219, v219, v225, v229
	v_max3_f32 v221, v153, v154, v155
	v_max3_f32 v225, v169, v170, v171
	v_max3_f32 v223, v156, v157, v158
	v_max3_f32 v229, v172, v173, v174
	v_max3_f32 v221, v221, v223, v159
	v_max3_f32 v225, v225, v229, v175
	v_max_f32_e32 v217, v217, v221
	v_max_f32_e32 v219, v219, v225
	v_add_f32_e32 v221, v200, v217
	v_add_f32_e32 v225, v200, v219
	v_sub_f32_e32 v223, v221, v227
	v_sub_f32_e32 v229, v225, v215
	v_max_f32_e32 v223, v223, v229
	v_add_f32_e32 v223, 0x43080000, v223
	v_cmp_nlt_f32_e64 s[98:99], v223, 0
	s_nop 3
	s_cmp_eq_u64 s[98:99], 0
	s_cbranch_scc1 .Lat2_skip
	s_mov_b32 s51, 0
	ds_read_b64_tr_b16 v[202:203], v216
	ds_read_b64_tr_b16 v[204:205], v218
	ds_read_b64_tr_b16 v[244:245], v220
	ds_read_b64_tr_b16 v[246:247], v222
	ds_read_b64_tr_b16 v[248:249], v224
	ds_read_b64_tr_b16 v[250:251], v226
	ds_read_b64_tr_b16 v[252:253], v228
	ds_read_b64_tr_b16 v[254:255], v230
	s_branch .Lat2_go
.Lat3_probe:
	ds_read_b128 v[160:163], v237 offset:24576
	ds_read_b128 v[164:167], v189
	ds_read_b128 v[202:205], v235 offset:24576
	ds_read_b128 v[244:247], v189 offset:4096
	ds_read_b128 v[248:251], v236 offset:24576
	ds_read_b128 v[252:255], v189 offset:1024
	s_waitcnt lgkmcnt(4)
	v_mfma_f32_32x32x16_bf16 v[144:159], v[160:163], v[164:167], v[128:143]
	s_waitcnt lgkmcnt(2)
	v_mfma_f32_32x32x16_bf16 v[160:175], v[202:205], v[244:247], v[128:143]
	ds_read_b128 v[202:205], v234 offset:24576
	ds_read_b128 v[244:247], v189 offset:5120
	v_add_u32_e32 v215, s40, v185
	v_add_u32_e32 v215, 0xa0, v215
	v_cvt_f32_i32_e32 v215, v215
	v_add_f32_e32 v227, 0x41000000, v199
	v_mul_f32_e32 v200, v184, v215
	v_add_f32_e32 v215, 0x41000000, v201
	s_waitcnt lgkmcnt(2)
	v_mfma_f32_32x32x16_bf16 v[144:159], v[248:251], v[252:255], v[144:159]
	ds_read_b128 v[248:251], v241 offset:24576
	ds_read_b128 v[252:255], v189 offset:2048
	s_waitcnt lgkmcnt(2)
	v_mfma_f32_32x32x16_bf16 v[160:175], v[202:205], v[244:247], v[160:175]
	ds_read_b128 v[202:205], v239 offset:24576
	ds_read_b128 v[244:247], v189 offset:6144
	s_waitcnt lgkmcnt(2)
	v_mfma_f32_32x32x16_bf16 v[144:159], v[248:251], v[252:255], v[144:159]
	ds_read_b128 v[248:251], v240 offset:24576
	ds_read_b128 v[252:255], v189 offset:3072
	s_waitcnt lgkmcnt(2)
	v_mfma_f32_32x32x16_bf16 v[160:175], v[202:205], v[244:247], v[160:175]
	ds_read_b128 v[202:205], v238 offset:24576
	ds_read_b128 v[244:247], v189 offset:7168
	s_waitcnt lgkmcnt(2)
	v_mfma_f32_32x32x16_bf16 v[144:159], v[248:251], v[252:255], v[144:159]
	s_waitcnt lgkmcnt(0)
	v_mfma_f32_32x32x16_bf16 v[160:175], v[202:205], v[244:247], v[160:175]
	s_nop 7
	s_nop 7
	v_max3_f32 v217, v144, v145, v146
	v_max3_f32 v219, v160, v161, v162
	v_max3_f32 v221, v147, v148, v149
	v_max3_f32 v225, v163, v164, v165
	v_max3_f32 v223, v150, v151, v152
	v_max3_f32 v229, v166, v167, v168
	v_max3_f32 v217, v217, v221, v223
	v_max3_f32 v219, v219, v225, v229
	v_max3_f32 v221, v153, v154, v155
	v_max3_f32 v225, v169, v170, v171
	v_max3_f32 v223, v156, v157, v158
	v_max3_f32 v229, v172, v173, v174
	v_max3_f32 v221, v221, v223, v159
	v_max3_f32 v225, v225, v229, v175
	v_max_f32_e32 v217, v217, v221
	v_max_f32_e32 v219, v219, v225
	v_add_f32_e32 v221, v200, v217
	v_add_f32_e32 v225, v200, v219
	v_sub_f32_e32 v223, v221, v227
	v_sub_f32_e32 v229, v225, v215
	v_max_f32_e32 v223, v223, v229
	v_add_f32_e32 v223, 0x43080000, v223
	v_cmp_nlt_f32_e64 s[98:99], v223, 0
	s_nop 3
	s_cmp_eq_u64 s[98:99], 0
	s_cbranch_scc1 .Lat3_skip
	s_mov_b32 s51, 0
	ds_read_b64_tr_b16 v[202:203], v216 offset:24576
	ds_read_b64_tr_b16 v[204:205], v218 offset:24576
	ds_read_b64_tr_b16 v[244:245], v220 offset:24576
	ds_read_b64_tr_b16 v[246:247], v222 offset:24576
	ds_read_b64_tr_b16 v[248:249], v224 offset:24576
	ds_read_b64_tr_b16 v[250:251], v226 offset:24576
	ds_read_b64_tr_b16 v[252:253], v228 offset:24576
	ds_read_b64_tr_b16 v[254:255], v230 offset:24576
	s_branch .Lat3_go
.Lat4_probe:
	ds_read_b128 v[160:163], v237 offset:16384
	ds_read_b128 v[164:167], v189
	ds_read_b128 v[202:205], v235 offset:16384
	ds_read_b128 v[244:247], v189 offset:4096
	ds_read_b128 v[248:251], v236 offset:16384
	ds_read_b128 v[252:255], v189 offset:1024
	s_waitcnt lgkmcnt(4)
	v_mfma_f32_32x32x16_bf16 v[144:159], v[160:163], v[164:167], v[128:143]
	s_waitcnt lgkmcnt(2)
	v_mfma_f32_32x32x16_bf16 v[160:175], v[202:205], v[244:247], v[128:143]
	ds_read_b128 v[202:205], v234 offset:16384
	ds_read_b128 v[244:247], v189 offset:5120
	v_add_u32_e32 v215, s40, v185
	v_add_u32_e32 v215, 0x80, v215
	v_cvt_f32_i32_e32 v215, v215
	v_add_f32_e32 v227, 0x41000000, v199
	v_mul_f32_e32 v200, v184, v215
	v_add_f32_e32 v215, 0x41000000, v201
	s_waitcnt lgkmcnt(2)
	v_mfma_f32_32x32x16_bf16 v[144:159], v[248:251], v[252:255], v[144:159]
	ds_read_b128 v[248:251], v241 offset:16384
	ds_read_b128 v[252:255], v189 offset:2048
	s_waitcnt lgkmcnt(2)
	v_mfma_f32_32x32x16_bf16 v[160:175], v[202:205], v[244:247], v[160:175]
	ds_read_b128 v[202:205], v239 offset:16384
	ds_read_b128 v[244:247], v189 offset:6144
	s_waitcnt lgkmcnt(2)
	v_mfma_f32_32x32x16_bf16 v[144:159], v[248:251], v[252:255], v[144:159]
	ds_read_b128 v[248:251], v240 offset:16384
	ds_read_b128 v[252:255], v189 offset:3072
	s_waitcnt lgkmcnt(2)
	v_mfma_f32_32x32x16_bf16 v[160:175], v[202:205], v[244:247], v[160:175]
	ds_read_b128 v[202:205], v238 offset:16384
	ds_read_b128 v[244:247], v189 offset:7168
	s_waitcnt lgkmcnt(2)
	v_mfma_f32_32x32x16_bf16 v[144:159], v[248:251], v[252:255], v[144:159]
	s_waitcnt lgkmcnt(0)
	v_mfma_f32_32x32x16_bf16 v[160:175], v[202:205], v[244:247], v[160:175]
	s_nop 7
	s_nop 7
	v_max3_f32 v217, v144, v145, v146
	v_max3_f32 v219, v160, v161, v162
	v_max3_f32 v221, v147, v148, v149
	v_max3_f32 v225, v163, v164, v165
	v_max3_f32 v223, v150, v151, v152
	v_max3_f32 v229, v166, v167, v168
	v_max3_f32 v217, v217, v221, v223
	v_max3_f32 v219, v219, v225, v229
	v_max3_f32 v221, v153, v154, v155
	v_max3_f32 v225, v169, v170, v171
	v_max3_f32 v223, v156, v157, v158
	v_max3_f32 v229, v172, v173, v174
	v_max3_f32 v221, v221, v223, v159
	v_max3_f32 v225, v225, v229, v175
	v_max_f32_e32 v217, v217, v221
	v_max_f32_e32 v219, v219, v225
	v_add_f32_e32 v221, v200, v217
	v_add_f32_e32 v225, v200, v219
	v_sub_f32_e32 v223, v221, v227
	v_sub_f32_e32 v229, v225, v215
	v_max_f32_e32 v223, v223, v229
	v_add_f32_e32 v223, 0x43080000, v223
	v_cmp_nlt_f32_e64 s[98:99], v223, 0
	s_nop 3
	s_cmp_eq_u64 s[98:99], 0
	s_cbranch_scc1 .Lat4_skip
	s_mov_b32 s51, 0
	ds_read_b64_tr_b16 v[202:203], v216 offset:16384
	ds_read_b64_tr_b16 v[204:205], v218 offset:16384
	ds_read_b64_tr_b16 v[244:245], v220 offset:16384
	ds_read_b64_tr_b16 v[246:247], v222 offset:16384
	ds_read_b64_tr_b16 v[248:249], v224 offset:16384
	ds_read_b64_tr_b16 v[250:251], v226 offset:16384
	ds_read_b64_tr_b16 v[252:253], v228 offset:16384
	ds_read_b64_tr_b16 v[254:255], v230 offset:16384
	s_branch .Lat4_go
.Lat5_probe:
	ds_read_b128 v[160:163], v237 offset:40960
	ds_read_b128 v[164:167], v189
	ds_read_b128 v[202:205], v235 offset:40960
	ds_read_b128 v[244:247], v189 offset:4096
	ds_read_b128 v[248:251], v236 offset:40960
	ds_read_b128 v[252:255], v189 offset:1024
	s_waitcnt lgkmcnt(4)
	v_mfma_f32_32x32x16_bf16 v[144:159], v[160:163], v[164:167], v[128:143]
	s_waitcnt lgkmcnt(2)
	v_mfma_f32_32x32x16_bf16 v[160:175], v[202:205], v[244:247], v[128:143]
	ds_read_b128 v[202:205], v234 offset:40960
	ds_read_b128 v[244:247], v189 offset:5120
	v_add_u32_e32 v215, s40, v185
	v_add_u32_e32 v215, 0x60, v215
	v_cvt_f32_i32_e32 v215, v215
	v_add_f32_e32 v227, 0x41000000, v199
	v_mul_f32_e32 v200, v184, v215
	v_add_f32_e32 v215, 0x41000000, v201
	s_waitcnt lgkmcnt(2)
	v_mfma_f32_32x32x16_bf16 v[144:159], v[248:251], v[252:255], v[144:159]
	ds_read_b128 v[248:251], v241 offset:40960
	ds_read_b128 v[252:255], v189 offset:2048
	s_waitcnt lgkmcnt(2)
	v_mfma_f32_32x32x16_bf16 v[160:175], v[202:205], v[244:247], v[160:175]
	ds_read_b128 v[202:205], v239 offset:40960
	ds_read_b128 v[244:247], v189 offset:6144
	s_waitcnt lgkmcnt(2)
	v_mfma_f32_32x32x16_bf16 v[144:159], v[248:251], v[252:255], v[144:159]
	ds_read_b128 v[248:251], v240 offset:40960
	ds_read_b128 v[252:255], v189 offset:3072
	s_waitcnt lgkmcnt(2)
	v_mfma_f32_32x32x16_bf16 v[160:175], v[202:205], v[244:247], v[160:175]
	ds_read_b128 v[202:205], v238 offset:40960
	ds_read_b128 v[244:247], v189 offset:7168
	s_waitcnt lgkmcnt(2)
	v_mfma_f32_32x32x16_bf16 v[144:159], v[248:251], v[252:255], v[144:159]
	s_waitcnt lgkmcnt(0)
	v_mfma_f32_32x32x16_bf16 v[160:175], v[202:205], v[244:247], v[160:175]
	s_nop 7
	s_nop 7
	v_max3_f32 v217, v144, v145, v146
	v_max3_f32 v219, v160, v161, v162
	v_max3_f32 v221, v147, v148, v149
	v_max3_f32 v225, v163, v164, v165
	v_max3_f32 v223, v150, v151, v152
	v_max3_f32 v229, v166, v167, v168
	v_max3_f32 v217, v217, v221, v223
	v_max3_f32 v219, v219, v225, v229
	v_max3_f32 v221, v153, v154, v155
	v_max3_f32 v225, v169, v170, v171
	v_max3_f32 v223, v156, v157, v158
	v_max3_f32 v229, v172, v173, v174
	v_max3_f32 v221, v221, v223, v159
	v_max3_f32 v225, v225, v229, v175
	v_max_f32_e32 v217, v217, v221
	v_max_f32_e32 v219, v219, v225
	v_add_f32_e32 v221, v200, v217
	v_add_f32_e32 v225, v200, v219
	v_sub_f32_e32 v223, v221, v227
	v_sub_f32_e32 v229, v225, v215
	v_max_f32_e32 v223, v223, v229
	v_add_f32_e32 v223, 0x43080000, v223
	v_cmp_nlt_f32_e64 s[98:99], v223, 0
	s_nop 3
	s_cmp_eq_u64 s[98:99], 0
	s_cbranch_scc1 .Lat5_skip
	s_mov_b32 s51, 0
	ds_read_b64_tr_b16 v[202:203], v216 offset:40960
	ds_read_b64_tr_b16 v[204:205], v218 offset:40960
	ds_read_b64_tr_b16 v[244:245], v220 offset:40960
	ds_read_b64_tr_b16 v[246:247], v222 offset:40960
	ds_read_b64_tr_b16 v[248:249], v224 offset:40960
	ds_read_b64_tr_b16 v[250:251], v226 offset:40960
	ds_read_b64_tr_b16 v[252:253], v228 offset:40960
	ds_read_b64_tr_b16 v[254:255], v230 offset:40960
	s_branch .Lat5_go
.Lat6_probe:
	ds_read_b128 v[160:163], v237 offset:32768
	ds_read_b128 v[164:167], v189
	ds_read_b128 v[202:205], v235 offset:32768
	ds_read_b128 v[244:247], v189 offset:4096
	ds_read_b128 v[248:251], v236 offset:32768
	ds_read_b128 v[252:255], v189 offset:1024
	s_waitcnt lgkmcnt(4)
	v_mfma_f32_32x32x16_bf16 v[144:159], v[160:163], v[164:167], v[128:143]
	s_waitcnt lgkmcnt(2)
	v_mfma_f32_32x32x16_bf16 v[160:175], v[202:205], v[244:247], v[128:143]
	ds_read_b128 v[202:205], v234 offset:32768
	ds_read_b128 v[244:247], v189 offset:5120
	v_add_u32_e32 v215, s40, v185
	v_add_u32_e32 v215, 0x40, v215
	v_cvt_f32_i32_e32 v215, v215
	v_add_f32_e32 v227, 0x41000000, v199
	v_mul_f32_e32 v200, v184, v215
	v_add_f32_e32 v215, 0x41000000, v201
	s_waitcnt lgkmcnt(2)
	v_mfma_f32_32x32x16_bf16 v[144:159], v[248:251], v[252:255], v[144:159]
	ds_read_b128 v[248:251], v241 offset:32768
	ds_read_b128 v[252:255], v189 offset:2048
	s_waitcnt lgkmcnt(2)
	v_mfma_f32_32x32x16_bf16 v[160:175], v[202:205], v[244:247], v[160:175]
	ds_read_b128 v[202:205], v239 offset:32768
	ds_read_b128 v[244:247], v189 offset:6144
	s_waitcnt lgkmcnt(2)
	v_mfma_f32_32x32x16_bf16 v[144:159], v[248:251], v[252:255], v[144:159]
	ds_read_b128 v[248:251], v240 offset:32768
	ds_read_b128 v[252:255], v189 offset:3072
	s_waitcnt lgkmcnt(2)
	v_mfma_f32_32x32x16_bf16 v[160:175], v[202:205], v[244:247], v[160:175]
	ds_read_b128 v[202:205], v238 offset:32768
	ds_read_b128 v[244:247], v189 offset:7168
	s_waitcnt lgkmcnt(2)
	v_mfma_f32_32x32x16_bf16 v[144:159], v[248:251], v[252:255], v[144:159]
	s_waitcnt lgkmcnt(0)
	v_mfma_f32_32x32x16_bf16 v[160:175], v[202:205], v[244:247], v[160:175]
	s_nop 7
	s_nop 7
	v_max3_f32 v217, v144, v145, v146
	v_max3_f32 v219, v160, v161, v162
	v_max3_f32 v221, v147, v148, v149
	v_max3_f32 v225, v163, v164, v165
	v_max3_f32 v223, v150, v151, v152
	v_max3_f32 v229, v166, v167, v168
	v_max3_f32 v217, v217, v221, v223
	v_max3_f32 v219, v219, v225, v229
	v_max3_f32 v221, v153, v154, v155
	v_max3_f32 v225, v169, v170, v171
	v_max3_f32 v223, v156, v157, v158
	v_max3_f32 v229, v172, v173, v174
	v_max3_f32 v221, v221, v223, v159
	v_max3_f32 v225, v225, v229, v175
	v_max_f32_e32 v217, v217, v221
	v_max_f32_e32 v219, v219, v225
	v_add_f32_e32 v221, v200, v217
	v_add_f32_e32 v225, v200, v219
	v_sub_f32_e32 v223, v221, v227
	v_sub_f32_e32 v229, v225, v215
	v_max_f32_e32 v223, v223, v229
	v_add_f32_e32 v223, 0x43080000, v223
	v_cmp_nlt_f32_e64 s[98:99], v223, 0
	s_nop 3
	s_cmp_eq_u64 s[98:99], 0
	s_cbranch_scc1 .Lat6_skip
	s_mov_b32 s51, 0
	ds_read_b64_tr_b16 v[202:203], v216 offset:32768
	ds_read_b64_tr_b16 v[204:205], v218 offset:32768
	ds_read_b64_tr_b16 v[244:245], v220 offset:32768
	ds_read_b64_tr_b16 v[246:247], v222 offset:32768
	ds_read_b64_tr_b16 v[248:249], v224 offset:32768
	ds_read_b64_tr_b16 v[250:251], v226 offset:32768
	ds_read_b64_tr_b16 v[252:253], v228 offset:32768
	ds_read_b64_tr_b16 v[254:255], v230 offset:32768
	s_branch .Lat6_go
